# v13 + FFN1 meta-row skinny GEMM moved behind the gate|up GEMM units (runs when HBM is quiet)
# speedup vs baseline: 1.0020x; 1.0020x over previous
.LBB0_117:
	s_or_b64 exec, exec, s[6:7]
	s_waitcnt vmcnt(0)
	buffer_inv sc1
	s_waitcnt vmcnt(0)
.LBB0_118:
	s_or_b64 exec, exec, s[2:3]
	s_barrier
.LBB0_123:
	s_mov_b64 s[2:3], s[90:91]
	v_mbcnt_lo_u32_b32 v8, -1, 0
	v_mbcnt_hi_u32_b32 v8, -1, v8
	s_cmpk_gt_i32 s22, 0x157f
	v_add_u32_e32 v0, s74, v8
	s_nop 0
	v_readfirstlane_b32 s10, v0
	s_cbranch_scc1 .LBB0_143
	s_load_dwordx2 s[8:9], s[2:3], 0xc8
	s_movk_i32 s0, 0x2b1
	v_and_b32_e32 v1, 63, v8
	v_lshlrev_b32_e32 v128, 4, v1
	s_waitcnt lgkmcnt(0)
	s_add_u32 s2, s8, 0x600000
	s_addc_u32 s3, s9, 0
	s_ashr_i32 s23, s22, 31
	s_lshr_b32 s1, s23, 29
	s_add_i32 s1, s22, s1
	s_ashr_i32 s4, s1, 3
	s_and_b32 s1, s1, -8
	s_sub_i32 s1, s22, s1
	s_cmp_lt_i32 s1, 0
	s_cselect_b32 s0, s0, 0x2b0
	s_mul_i32 s0, s1, s0
	s_add_i32 s0, s0, s4
	s_mul_hi_i32 s1, s0, 0x2fa0be83
	s_lshr_b32 s4, s1, 31
	s_ashr_i32 s1, s1, 7
	s_add_i32 s1, s1, s4
	s_lshl_b32 s4, s1, 3
	s_mulk_i32 s1, 0x2b0
	s_sub_i32 s0, s0, s1
	s_sext_i32_i16 s1, s0
	s_bfe_u32 s1, s1, 0x3001c
	s_add_i32 s1, s0, s1
	s_sext_i32_i16 s5, s1
	s_and_b32 s1, s1, 0xfff8
	s_sub_i32 s0, s0, s1
	s_sext_i32_i16 s0, s0
	s_lshr_b32 s6, s5, 3
	s_add_i32 s28, s4, s0
	s_cmp_lt_u32 s10, 64
	s_cselect_b64 s[4:5], -1, 0
	s_ashr_i32 s29, s28, 31
	s_cmp_gt_u32 s10, 63
	s_cbranch_scc1 .LBB0_126
	s_lshl_b64 s[12:13], s[28:29], 10
	s_add_u32 s12, s2, s12
	s_addc_u32 s13, s3, s13
	s_add_i32 m0, 0, 0x20000
	s_nop 0
	global_load_lds_dwordx4 v128, s[12:13]

.LBB0_143:
	s_mov_b64 s[2:3], s[90:91]
	s_cmpk_gt_i32 s22, 0x2af
	v_mbcnt_lo_u32_b32 v1, -1, 0
	v_mbcnt_hi_u32_b32 v1, -1, v1
	s_cbranch_scc1 .Lsk_done
	s_load_dwordx2 s[4:5], s[2:3], 0xc8
	v_and_b32_e32 v2, 15, v1
	v_and_b32_e32 v0, -16, v1
	v_lshlrev_b32_e32 v3, 13, v2
	v_or_b32_e32 v68, 0x4000, v2
	s_waitcnt lgkmcnt(0)
	s_add_u32 s8, s4, 0x800000
	s_addc_u32 s9, s5, 0
	s_lshl_b32 s0, s81, 10
	s_lshl_b32 s10, s81, 11
	s_cmp_lt_u32 s61, 64
	v_lshl_add_u32 v70, v1, 4, 0
	v_add3_u32 v0, v0, s0, v3
	s_cselect_b64 s[2:3], -1, 0
	v_ashrrev_i32_e32 v1, 2, v1
	v_lshlrev_b32_e32 v2, 13, v68
	v_mov_b32_e32 v3, 0
	s_add_u32 s6, s4, 0x27600000
	v_and_b32_e32 v71, -4, v1
	v_mov_b32_e32 v1, v3
	s_waitcnt vmcnt(4)
	v_add_u32_e32 v4, 64, v0
	v_mov_b32_e32 v5, v3
	v_add_u32_e32 v6, 0x80, v0
	v_mov_b32_e32 v7, v3
	v_add_u32_e32 v8, 0xc0, v0
	v_mov_b32_e32 v9, v3
	v_add_u32_e32 v10, 0x100, v0
	v_mov_b32_e32 v11, v3
	v_add_u32_e32 v12, 0x140, v0
	v_mov_b32_e32 v13, v3
	v_add_u32_e32 v14, 0x180, v0
	v_mov_b32_e32 v15, v3
	v_add_u32_e32 v16, 0x1c0, v0
	v_mov_b32_e32 v17, v3
	v_add_u32_e32 v18, 0x200, v0
	v_mov_b32_e32 v19, v3
	v_add_u32_e32 v20, 0x240, v0
	v_mov_b32_e32 v21, v3
	v_add_u32_e32 v22, 0x280, v0
	v_mov_b32_e32 v23, v3
	v_add_u32_e32 v24, 0x2c0, v0
	v_mov_b32_e32 v25, v3
	v_add_u32_e32 v26, 0x300, v0
	v_mov_b32_e32 v27, v3
	v_add_u32_e32 v28, 0x340, v0
	v_mov_b32_e32 v29, v3
	v_add_u32_e32 v30, 0x380, v0
	v_mov_b32_e32 v31, v3
	v_add_u32_e32 v32, 0x3c0, v0
	v_mov_b32_e32 v33, v3
	s_addc_u32 s7, s5, 0
	v_lshl_add_u64 v[66:67], s[4:5], 0, v[2:3]
	v_lshlrev_b32_e32 v2, 2, v68
	v_lshl_add_u64 v[34:35], s[6:7], 0, v[0:1]
	v_lshl_add_u64 v[36:37], s[6:7], 0, v[4:5]
	v_lshl_add_u64 v[38:39], s[6:7], 0, v[6:7]
	v_lshl_add_u64 v[40:41], s[6:7], 0, v[8:9]
	v_lshl_add_u64 v[42:43], s[6:7], 0, v[10:11]
	v_lshl_add_u64 v[44:45], s[6:7], 0, v[12:13]
	v_lshl_add_u64 v[46:47], s[6:7], 0, v[14:15]
	v_lshl_add_u64 v[48:49], s[6:7], 0, v[16:17]
	v_lshl_add_u64 v[50:51], s[6:7], 0, v[18:19]
	v_lshl_add_u64 v[52:53], s[6:7], 0, v[20:21]
	v_lshl_add_u64 v[54:55], s[6:7], 0, v[22:23]
	v_lshl_add_u64 v[56:57], s[6:7], 0, v[24:25]
	v_lshl_add_u64 v[58:59], s[6:7], 0, v[26:27]
	v_lshl_add_u64 v[60:61], s[6:7], 0, v[28:29]
	v_lshl_add_u64 v[62:63], s[6:7], 0, v[30:31]
	v_lshl_add_u64 v[64:65], s[6:7], 0, v[32:33]
	s_mov_b64 s[6:7], 0x2fa00000
	v_lshl_add_u64 v[68:69], s[4:5], 0, v[2:3]
	s_mov_b64 s[4:5], 0x600000
	v_lshl_add_u64 v[66:67], v[66:67], 0, s[6:7]
	v_lshl_add_u64 v[68:69], v[68:69], 0, s[4:5]
	s_lshl_b32 s11, s22, 4
	s_lshl_b32 s12, s72, 4
	s_lshl_b32 s13, s22, 5
	s_lshl_b32 s14, s72, 5
	s_movk_i32 s15, 0x7fff
	s_mov_b32 s16, 0x8200000
	v_mov_b32_e32 v72, 1
	s_mov_b32 s17, s22
	global_load_dwordx4 v[4:7], v[34:35], off
	global_load_dwordx4 v[8:11], v[34:35], off offset:64
	global_load_dwordx4 v[12:15], v[34:35], off offset:128
	global_load_dwordx4 v[16:19], v[34:35], off offset:192
	global_load_dwordx4 v[20:23], v[34:35], off offset:256
	global_load_dwordx4 v[24:27], v[34:35], off offset:320
	global_load_dwordx4 v[28:31], v[34:35], off offset:384
	global_load_dwordx4 v[36:39], v[34:35], off offset:448
	global_load_dwordx4 v[40:43], v[34:35], off offset:512
	global_load_dwordx4 v[44:47], v[34:35], off offset:576
	global_load_dwordx4 v[48:51], v[34:35], off offset:640
	global_load_dwordx4 v[52:55], v[34:35], off offset:704
	global_load_dwordx4 v[56:59], v[34:35], off offset:768
	global_load_dwordx4 v[60:63], v[34:35], off offset:832
	global_load_dwordx4 v[246:249], v[34:35], off offset:896
	global_load_dwordx4 v[250:253], v[34:35], off offset:960
	v_mbcnt_lo_u32_b32 v2, -1, 0
	v_mbcnt_hi_u32_b32 v2, -1, v2
	v_lshrrev_b32_e32 v34, 5, v2
	v_and_b32_e32 v35, 31, v2
	v_lshlrev_b32_e32 v32, 13, v34
	v_lshl_add_u32 v32, v35, 4, v32
	s_lshl_b32 s0, s81, 10
	v_add_u32_e32 v32, s0, v32
	v_add_u32_e32 v33, 0x4000, v32
	v_add_u32_e32 v64, 0x8000, v32
	v_add_u32_e32 v65, 0xc000, v32
	v_add_u32_e32 v242, 0x10000, v32
	v_add_u32_e32 v243, 0x14000, v32
	v_add_u32_e32 v244, 0x18000, v32
	v_add_u32_e32 v245, 0x1c000, v32
	s_mul_i32 s0, s81, 0x2100
	s_add_i32 s0, s0, 0x4000
	v_mul_u32_u24_e32 v34, 0x210, v34
	v_lshl_add_u32 v34, v35, 4, v34
	v_add_u32_e32 v34, s0, v34
	v_and_b32_e32 v35, 15, v2
	v_mul_u32_u24_e32 v35, 0x210, v35
	v_lshrrev_b32_e32 v2, 4, v2
	v_lshl_add_u32 v35, v2, 4, v35
	v_add_u32_e32 v35, s0, v35
	s_branch .LBB0_121

.LBB0_121:
	s_and_b32 s0, s13, 0xffffff00
	s_and_b32 s1, s11, 0x70
	s_or_b32 s4, s0, s1
	s_ashr_i32 s5, s4, 31
	s_lshl_b64 s[4:5], s[4:5], 13
	s_add_u32 s4, s8, s4
	s_addc_u32 s5, s9, s5
	s_add_u32 s6, s4, 0x100000
	s_addc_u32 s7, s5, 0
	v_add_u32_e32 v2, s10, v70
	s_andn2_b64 vcc, exec, s[2:3]
	global_load_dwordx4 v[82:85], v32, s[4:5]
	global_load_dwordx4 v[86:89], v33, s[4:5]
	global_load_dwordx4 v[90:93], v64, s[4:5]
	global_load_dwordx4 v[94:97], v65, s[4:5]
	global_load_dwordx4 v[98:101], v242, s[4:5]
	global_load_dwordx4 v[102:105], v243, s[4:5]
	global_load_dwordx4 v[106:109], v244, s[4:5]
	global_load_dwordx4 v[110:113], v245, s[4:5]
	global_load_dwordx4 v[114:117], v32, s[4:5] offset:512
	global_load_dwordx4 v[118:121], v33, s[4:5] offset:512
	global_load_dwordx4 v[122:125], v64, s[4:5] offset:512
	global_load_dwordx4 v[126:129], v65, s[4:5] offset:512
	global_load_dwordx4 v[130:133], v242, s[4:5] offset:512
	global_load_dwordx4 v[134:137], v243, s[4:5] offset:512
	global_load_dwordx4 v[138:141], v244, s[4:5] offset:512
	global_load_dwordx4 v[142:145], v245, s[4:5] offset:512
	global_load_dwordx4 v[146:149], v32, s[6:7]
	global_load_dwordx4 v[150:153], v33, s[6:7]
	global_load_dwordx4 v[154:157], v64, s[6:7]
	global_load_dwordx4 v[158:161], v65, s[6:7]
	global_load_dwordx4 v[162:165], v242, s[6:7]
	global_load_dwordx4 v[166:169], v243, s[6:7]
	global_load_dwordx4 v[170:173], v244, s[6:7]
	global_load_dwordx4 v[174:177], v245, s[6:7]
	global_load_dwordx4 v[178:181], v32, s[6:7] offset:512
	global_load_dwordx4 v[182:185], v33, s[6:7] offset:512
	global_load_dwordx4 v[186:189], v64, s[6:7] offset:512
	global_load_dwordx4 v[190:193], v65, s[6:7] offset:512
	global_load_dwordx4 v[194:197], v242, s[6:7] offset:512
	global_load_dwordx4 v[198:201], v243, s[6:7] offset:512
	global_load_dwordx4 v[202:205], v244, s[6:7] offset:512
	global_load_dwordx4 v[206:209], v245, s[6:7] offset:512
	s_waitcnt vmcnt(31)
	ds_write_b128 v34, v[82:85]
	s_waitcnt vmcnt(30)
	ds_write_b128 v34, v[86:89] offset:1056
	s_waitcnt vmcnt(29)
	ds_write_b128 v34, v[90:93] offset:2112
	s_waitcnt vmcnt(28)
	ds_write_b128 v34, v[94:97] offset:3168
	s_waitcnt vmcnt(27)
	ds_write_b128 v34, v[98:101] offset:4224
	s_waitcnt vmcnt(26)
	ds_write_b128 v34, v[102:105] offset:5280
	s_waitcnt vmcnt(25)
	ds_write_b128 v34, v[106:109] offset:6336
	s_waitcnt vmcnt(24)
	ds_write_b128 v34, v[110:113] offset:7392
	s_waitcnt lgkmcnt(0)
	ds_read_b128 v[210:213], v35
	ds_read_b128 v[214:217], v35 offset:64
	ds_read_b128 v[218:221], v35 offset:128
	ds_read_b128 v[222:225], v35 offset:192
	ds_read_b128 v[226:229], v35 offset:256
	ds_read_b128 v[230:233], v35 offset:320
	ds_read_b128 v[234:237], v35 offset:384
	ds_read_b128 v[238:241], v35 offset:448
	s_waitcnt lgkmcnt(7)
	v_mfma_f32_16x16x32_bf16 v[74:77], v[210:213], v[4:7], 0
	s_waitcnt lgkmcnt(6)
	v_mfma_f32_16x16x32_bf16 v[74:77], v[214:217], v[8:11], v[74:77]
	s_waitcnt lgkmcnt(5)
	v_mfma_f32_16x16x32_bf16 v[74:77], v[218:221], v[12:15], v[74:77]
	s_waitcnt lgkmcnt(4)
	v_mfma_f32_16x16x32_bf16 v[74:77], v[222:225], v[16:19], v[74:77]
	s_waitcnt lgkmcnt(3)
	v_mfma_f32_16x16x32_bf16 v[74:77], v[226:229], v[20:23], v[74:77]
	s_waitcnt lgkmcnt(2)
	v_mfma_f32_16x16x32_bf16 v[74:77], v[230:233], v[24:27], v[74:77]
	s_waitcnt lgkmcnt(1)
	v_mfma_f32_16x16x32_bf16 v[74:77], v[234:237], v[28:31], v[74:77]
	s_waitcnt lgkmcnt(0)
	v_mfma_f32_16x16x32_bf16 v[74:77], v[238:241], v[36:39], v[74:77]
	s_waitcnt vmcnt(23)
	ds_write_b128 v34, v[114:117]
	s_waitcnt vmcnt(22)
	ds_write_b128 v34, v[118:121] offset:1056
	s_waitcnt vmcnt(21)
	ds_write_b128 v34, v[122:125] offset:2112
	s_waitcnt vmcnt(20)
	ds_write_b128 v34, v[126:129] offset:3168
	s_waitcnt vmcnt(19)
	ds_write_b128 v34, v[130:133] offset:4224
	s_waitcnt vmcnt(18)
	ds_write_b128 v34, v[134:137] offset:5280
	s_waitcnt vmcnt(17)
	ds_write_b128 v34, v[138:141] offset:6336
	s_waitcnt vmcnt(16)
	ds_write_b128 v34, v[142:145] offset:7392
	s_waitcnt lgkmcnt(0)
	ds_read_b128 v[210:213], v35
	ds_read_b128 v[214:217], v35 offset:64
	ds_read_b128 v[218:221], v35 offset:128
	ds_read_b128 v[222:225], v35 offset:192
	ds_read_b128 v[226:229], v35 offset:256
	ds_read_b128 v[230:233], v35 offset:320
	ds_read_b128 v[234:237], v35 offset:384
	ds_read_b128 v[238:241], v35 offset:448
	s_waitcnt lgkmcnt(7)
	v_mfma_f32_16x16x32_bf16 v[74:77], v[210:213], v[40:43], v[74:77]
	s_waitcnt lgkmcnt(6)
	v_mfma_f32_16x16x32_bf16 v[74:77], v[214:217], v[44:47], v[74:77]
	s_waitcnt lgkmcnt(5)
	v_mfma_f32_16x16x32_bf16 v[74:77], v[218:221], v[48:51], v[74:77]
	s_waitcnt lgkmcnt(4)
	v_mfma_f32_16x16x32_bf16 v[74:77], v[222:225], v[52:55], v[74:77]
	s_waitcnt lgkmcnt(3)
	v_mfma_f32_16x16x32_bf16 v[74:77], v[226:229], v[56:59], v[74:77]
	s_waitcnt lgkmcnt(2)
	v_mfma_f32_16x16x32_bf16 v[74:77], v[230:233], v[60:63], v[74:77]
	s_waitcnt lgkmcnt(1)
	v_mfma_f32_16x16x32_bf16 v[74:77], v[234:237], v[246:249], v[74:77]
	s_waitcnt lgkmcnt(0)
	v_mfma_f32_16x16x32_bf16 v[74:77], v[238:241], v[250:253], v[74:77]
	s_waitcnt vmcnt(15)
	ds_write_b128 v34, v[146:149]
	s_waitcnt vmcnt(14)
	ds_write_b128 v34, v[150:153] offset:1056
	s_waitcnt vmcnt(13)
	ds_write_b128 v34, v[154:157] offset:2112
	s_waitcnt vmcnt(12)
	ds_write_b128 v34, v[158:161] offset:3168
	s_waitcnt vmcnt(11)
	ds_write_b128 v34, v[162:165] offset:4224
	s_waitcnt vmcnt(10)
	ds_write_b128 v34, v[166:169] offset:5280
	s_waitcnt vmcnt(9)
	ds_write_b128 v34, v[170:173] offset:6336
	s_waitcnt vmcnt(8)
	ds_write_b128 v34, v[174:177] offset:7392
	s_waitcnt lgkmcnt(0)
	ds_read_b128 v[210:213], v35
	ds_read_b128 v[214:217], v35 offset:64
	ds_read_b128 v[218:221], v35 offset:128
	ds_read_b128 v[222:225], v35 offset:192
	ds_read_b128 v[226:229], v35 offset:256
	ds_read_b128 v[230:233], v35 offset:320
	ds_read_b128 v[234:237], v35 offset:384
	ds_read_b128 v[238:241], v35 offset:448
	s_waitcnt lgkmcnt(7)
	v_mfma_f32_16x16x32_bf16 v[78:81], v[210:213], v[4:7], 0
	s_waitcnt lgkmcnt(6)
	v_mfma_f32_16x16x32_bf16 v[78:81], v[214:217], v[8:11], v[78:81]
	s_waitcnt lgkmcnt(5)
	v_mfma_f32_16x16x32_bf16 v[78:81], v[218:221], v[12:15], v[78:81]
	s_waitcnt lgkmcnt(4)
	v_mfma_f32_16x16x32_bf16 v[78:81], v[222:225], v[16:19], v[78:81]
	s_waitcnt lgkmcnt(3)
	v_mfma_f32_16x16x32_bf16 v[78:81], v[226:229], v[20:23], v[78:81]
	s_waitcnt lgkmcnt(2)
	v_mfma_f32_16x16x32_bf16 v[78:81], v[230:233], v[24:27], v[78:81]
	s_waitcnt lgkmcnt(1)
	v_mfma_f32_16x16x32_bf16 v[78:81], v[234:237], v[28:31], v[78:81]
	s_waitcnt lgkmcnt(0)
	v_mfma_f32_16x16x32_bf16 v[78:81], v[238:241], v[36:39], v[78:81]
	s_waitcnt vmcnt(7)
	ds_write_b128 v34, v[178:181]
	s_waitcnt vmcnt(6)
	ds_write_b128 v34, v[182:185] offset:1056
	s_waitcnt vmcnt(5)
	ds_write_b128 v34, v[186:189] offset:2112
	s_waitcnt vmcnt(4)
	ds_write_b128 v34, v[190:193] offset:3168
	s_waitcnt vmcnt(3)
	ds_write_b128 v34, v[194:197] offset:4224
	s_waitcnt vmcnt(2)
	ds_write_b128 v34, v[198:201] offset:5280
	s_waitcnt vmcnt(1)
	ds_write_b128 v34, v[202:205] offset:6336
	s_waitcnt vmcnt(0)
	ds_write_b128 v34, v[206:209] offset:7392
	s_waitcnt lgkmcnt(0)
	ds_read_b128 v[210:213], v35
	ds_read_b128 v[214:217], v35 offset:64
	ds_read_b128 v[218:221], v35 offset:128
	ds_read_b128 v[222:225], v35 offset:192
	ds_read_b128 v[226:229], v35 offset:256
	ds_read_b128 v[230:233], v35 offset:320
	ds_read_b128 v[234:237], v35 offset:384
	ds_read_b128 v[238:241], v35 offset:448
	s_waitcnt lgkmcnt(7)
	v_mfma_f32_16x16x32_bf16 v[78:81], v[210:213], v[40:43], v[78:81]
	s_waitcnt lgkmcnt(6)
	v_mfma_f32_16x16x32_bf16 v[78:81], v[214:217], v[44:47], v[78:81]
	s_waitcnt lgkmcnt(5)
	v_mfma_f32_16x16x32_bf16 v[78:81], v[218:221], v[48:51], v[78:81]
	s_waitcnt lgkmcnt(4)
	v_mfma_f32_16x16x32_bf16 v[78:81], v[222:225], v[52:55], v[78:81]
	s_waitcnt lgkmcnt(3)
	v_mfma_f32_16x16x32_bf16 v[78:81], v[226:229], v[56:59], v[78:81]
	s_waitcnt lgkmcnt(2)
	v_mfma_f32_16x16x32_bf16 v[78:81], v[230:233], v[60:63], v[78:81]
	s_waitcnt lgkmcnt(1)
	v_mfma_f32_16x16x32_bf16 v[78:81], v[234:237], v[246:249], v[78:81]
	s_waitcnt lgkmcnt(0)
	v_mfma_f32_16x16x32_bf16 v[78:81], v[238:241], v[250:253], v[78:81]
	s_nop 7
	ds_write_b128 v2, v[74:77]
	s_nop 0
	ds_write_b128 v2, v[78:81] offset:1024
	s_waitcnt lgkmcnt(0)
	s_waitcnt lgkmcnt(0)
	s_barrier
	s_cbranch_vccnz .LBB0_120
	global_load_dword v138, v[68:69], off
	ds_read_b128 v[74:77], v70
	ds_read_b128 v[78:81], v70 offset:1024
	ds_read_b128 v[82:85], v70 offset:2048
	ds_read_b128 v[86:89], v70 offset:3072
	ds_read_b128 v[90:93], v70 offset:4096
	ds_read_b128 v[94:97], v70 offset:5120
	ds_read_b128 v[98:101], v70 offset:6144
	ds_read_b128 v[102:105], v70 offset:7168
	ds_read_b128 v[106:109], v70 offset:8192
	ds_read_b128 v[110:113], v70 offset:9216
	ds_read_b128 v[114:117], v70 offset:10240
	ds_read_b128 v[118:121], v70 offset:11264
	ds_read_b128 v[122:125], v70 offset:12288
	ds_read_b128 v[126:129], v70 offset:13312
	ds_read_b128 v[130:133], v70 offset:14336
	ds_read_b128 v[134:137], v70 offset:15360
	s_waitcnt lgkmcnt(13)
	v_pk_add_f32 v[76:77], v[76:77], v[84:85]
	v_pk_add_f32 v[74:75], v[74:75], v[82:83]
	s_waitcnt lgkmcnt(12)
	v_pk_add_f32 v[78:79], v[78:79], v[86:87]
	s_waitcnt lgkmcnt(11)
	v_pk_add_f32 v[76:77], v[76:77], v[92:93]
	v_pk_add_f32 v[74:75], v[74:75], v[90:91]
	s_waitcnt lgkmcnt(10)
	v_pk_add_f32 v[78:79], v[78:79], v[94:95]
	s_waitcnt lgkmcnt(9)
	v_pk_add_f32 v[76:77], v[76:77], v[100:101]
	v_pk_add_f32 v[74:75], v[74:75], v[98:99]
	s_waitcnt lgkmcnt(8)
	v_pk_add_f32 v[78:79], v[78:79], v[102:103]
	s_waitcnt lgkmcnt(7)
	v_pk_add_f32 v[76:77], v[76:77], v[108:109]
	v_pk_add_f32 v[74:75], v[74:75], v[106:107]
	s_waitcnt lgkmcnt(6)
	v_pk_add_f32 v[78:79], v[78:79], v[110:111]
	s_waitcnt lgkmcnt(5)
	v_pk_add_f32 v[76:77], v[76:77], v[116:117]
	v_pk_add_f32 v[74:75], v[74:75], v[114:115]
	s_waitcnt lgkmcnt(4)
	v_pk_add_f32 v[78:79], v[78:79], v[118:119]
	s_waitcnt lgkmcnt(3)
	v_pk_add_f32 v[76:77], v[76:77], v[124:125]
	v_pk_add_f32 v[74:75], v[74:75], v[122:123]
	v_add_u32_e32 v2, s11, v71
	s_waitcnt lgkmcnt(2)
	v_pk_add_f32 v[78:79], v[78:79], v[126:127]
	s_waitcnt lgkmcnt(1)
	v_pk_add_f32 v[76:77], v[76:77], v[132:133]
	v_pk_add_f32 v[74:75], v[74:75], v[130:131]
	v_ashrrev_i32_e32 v73, 12, v2
	s_waitcnt lgkmcnt(0)
	v_pk_add_f32 v[78:79], v[78:79], v[134:135]
	v_mad_i64_i32 v[140:141], s[4:5], v73, s16, v[66:67]
	v_pk_add_f32 v[80:81], v[80:81], v[88:89]
	v_and_b32_e32 v2, 0xffc, v2
	v_pk_add_f32 v[80:81], v[80:81], v[96:97]
	v_lshlrev_b32_e32 v2, 1, v2
	v_pk_add_f32 v[80:81], v[80:81], v[104:105]
	s_waitcnt vmcnt(0)
	v_pk_mul_f32 v[76:77], v[76:77], v[138:139] op_sel_hi:[1,0]
	v_pk_mul_f32 v[74:75], v[74:75], v[138:139] op_sel_hi:[1,0]
	v_pk_mul_f32 v[78:79], v[78:79], v[138:139] op_sel_hi:[1,0]
	v_mul_f32_e32 v73, 0xbfb8aa3b, v74
	v_mul_f32_e32 v86, 0xbfb8aa3b, v75
	v_mul_f32_e32 v87, 0xbfb8aa3b, v76
	v_mul_f32_e32 v88, 0xbfb8aa3b, v77
	v_mov_b32_e32 v82, v74
	v_mov_b32_e32 v83, v76
	v_mov_b32_e32 v84, v78
	v_exp_f32_e32 v73, v73
	v_exp_f32_e32 v74, v86
	v_exp_f32_e32 v76, v87
	v_exp_f32_e32 v78, v88
	v_pk_add_f32 v[80:81], v[80:81], v[112:113]
	v_add_f32_e32 v73, 1.0, v73
	v_add_f32_e32 v74, 1.0, v74
	v_add_f32_e32 v76, 1.0, v76
	v_add_f32_e32 v78, 1.0, v78
	v_pk_add_f32 v[80:81], v[80:81], v[120:121]
	v_rcp_f32_e32 v86, v73
	v_rcp_f32_e32 v88, v74
	v_rcp_f32_e32 v87, v76
	v_rcp_f32_e32 v89, v78
	v_pk_add_f32 v[80:81], v[80:81], v[128:129]
	v_mov_b32_e32 v76, v75
	v_pk_add_f32 v[80:81], v[80:81], v[136:137]
	v_pk_mul_f32 v[74:75], v[82:83], v[86:87]
	v_pk_mul_f32 v[80:81], v[80:81], v[138:139] op_sel_hi:[1,0]
	v_pk_mul_f32 v[76:77], v[76:77], v[88:89]
	v_mov_b32_e32 v85, v80
	v_mov_b32_e32 v80, v79
	v_pk_mul_f32 v[74:75], v[84:85], v[74:75]
	v_pk_mul_f32 v[76:77], v[80:81], v[76:77]
	v_and_b32_sdwa v73, v75, v72 dst_sel:DWORD dst_unused:UNUSED_PAD src0_sel:WORD_1 src1_sel:DWORD
	v_and_b32_sdwa v79, v77, v72 dst_sel:DWORD dst_unused:UNUSED_PAD src0_sel:WORD_1 src1_sel:DWORD
	v_and_b32_sdwa v80, v76, v72 dst_sel:DWORD dst_unused:UNUSED_PAD src0_sel:WORD_1 src1_sel:DWORD
	v_and_b32_sdwa v78, v74, v72 dst_sel:DWORD dst_unused:UNUSED_PAD src0_sel:WORD_1 src1_sel:DWORD
	v_add3_u32 v73, v75, v73, s15
	v_add3_u32 v75, v77, v79, s15
	v_add3_u32 v76, v76, v80, s15
	v_add3_u32 v74, v74, v78, s15
	v_and_b32_e32 v75, 0xffff0000, v75
	v_and_b32_e32 v76, 0xffff0000, v76
	v_or_b32_sdwa v75, v75, v73 dst_sel:DWORD dst_unused:UNUSED_PAD src0_sel:DWORD src1_sel:WORD_1
	v_or_b32_sdwa v74, v76, v74 dst_sel:DWORD dst_unused:UNUSED_PAD src0_sel:DWORD src1_sel:WORD_1
	v_lshl_add_u64 v[76:77], v[140:141], 0, v[2:3]
	global_store_dwordx2 v[76:77], v[74:75], off
	s_branch .LBB0_120
.Lsk_done:
	s_mov_b64 s[2:3], s[90:91]
	v_mbcnt_lo_u32_b32 v18, -1, 0
	v_mbcnt_hi_u32_b32 v18, -1, v18
	s_load_dwordx2 s[30:31], s[2:3], 0xc8
	s_load_dwordx2 s[0:1], s[2:3], 0x88
	s_load_dwordx4 s[4:7], s[2:3], 0x38
	s_load_dwordx4 s[8:11], s[2:3], 0x78
	v_mov_b32_e32 v0, 0
	v_cmp_eq_u32_e64 s[2:3], 0, v18
	s_waitcnt lgkmcnt(0)
	v_writelane_b32 v255, s0, 2
	s_nop 1
	v_writelane_b32 v255, s1, 3
	s_add_u32 s0, s30, 0x8200
	s_addc_u32 s1, s31, 0
	v_writelane_b32 v255, s0, 4
	s_nop 1
	v_writelane_b32 v255, s1, 5
	s_and_saveexec_b64 s[18:19], s[2:3]
	s_cbranch_execz .LBB0_147
	s_mov_b64 s[28:29], exec
	v_mbcnt_lo_u32_b32 v0, s28, 0
	v_mbcnt_hi_u32_b32 v0, s29, v0
	v_cmp_eq_u32_e32 vcc, 0, v0
	s_and_saveexec_b64 s[20:21], vcc
	s_cbranch_execz .LBB0_146
	s_bcnt1_i32_b64 s0, s[28:29]
	s_lshl_b32 s0, s0, 4
	v_mov_b32_e32 v2, s0
	v_readlane_b32 s0, v255, 4
	v_mov_b32_e32 v1, 0
	v_readlane_b32 s1, v255, 5
	s_nop 4
	global_atomic_add v1, v1, v2, s[0:1] sc0
